# v051 + GLU epilogue Z-row loads as a rolling prefetch (10 in flight), counted waits derived from the issue order (9..15,15x4,14..10)
# baseline (speedup 1.0000x reference)
; #define GAS __attribute__((address_space(1)))
; __device__ __forceinline__ u32x4 pack8(f32x4 v0, f32x4 v1) { u32x4 w; w.x = cvt_pk_bf16(v0[0], v0[1]); w.y = cvt_pk_bf16(v0[2], v0[3]); w.z = cvt_pk_bf16(v1[0], v1[1]); w.w = cvt_pk_bf16(v1[2], v1[3]); return w; }
; __device__ __forceinline__ void unpack8(u32x4 w, f32x4& v0, f32x4& v1) { v0 = (f32x4){bflo(w.x), bfhi(w.x), bflo(w.y), bfhi(w.y)}; v1 = (f32x4){bflo(w.z), bfhi(w.z), bflo(w.w), bfhi(w.w)}; }
; #define GAS __attribute__((address_space(1)))
;     __device__ __forceinline__ void operator()(const f32x4 (&acc)[2][2][4][2], const Unit& u, int wr, int wc, int fr, int fq) const {
;         const int row0 = u.pm * BM + wr * 64 + fr, col0 = u.pn * BM + wc * 32 + 8 * fq;
;         f32x4 bv[2][2];
; #pragma unroll
;         for (int bj = 0; bj < 2; ++bj)
; #pragma unroll
;             for (int n = 0; n < 2; ++n) bv[bj][n] = *(const f32x4*)(bglu + col0 + bj * HALF + 4 * n);
;         const bf16_t* const zb = Z + (size_t)row0 * 1024 + col0; bf16_t* const sob = SO + (size_t)row0 * 1024 + col0;
; #pragma unroll
;         for (int ai = 0; ai < 2; ++ai)
; #pragma unroll
;             for (int m = 0; m < 4; ++m) { const size_t off = (size_t)(ai * HALF + m * 16) * 1024;
; #pragma unroll
;                 for (int bj = 0; bj < 2; ++bj) { f32x4 z0, z1; unpack8(*(const GAS u32x4*)(zb + off + bj * HALF), z0, z1);
;                     const f32x4 v0 = z0 * sigmoid4(acc[ai][bj][m][0] + bv[bj][0]), v1 = z1 * sigmoid4(acc[ai][bj][m][1] + bv[bj][1]);
;                     *(GAS u32x4*)(sob + off + bj * HALF) = pack8(v0, v1); } }
.LBB0_939:
	v_lshl_or_b32 v160, s24, 8, v164
	v_ashrrev_i32_e32 v161, 31, v160
	v_lshl_add_u64 v[22:23], v[160:161], 2, s[8:9]
	global_load_dwordx4 v[34:37], v[22:23], off offset:16
	global_load_dwordx4 v[38:41], v[22:23], off
	global_load_dwordx4 v[14:17], v[22:23], off offset:528
	s_nop 0
	global_load_dwordx4 v[22:25], v[22:23], off offset:512
	v_lshl_add_u32 v162, s42, 8, v1
	v_ashrrev_i32_e32 v163, 31, v162
	v_lshlrev_b64 v[166:167], 11, v[162:163]
	v_lshl_add_u64 v[162:163], s[4:5], 0, v[166:167]
	v_lshlrev_b64 v[160:161], 1, v[160:161]
	v_lshl_add_u64 v[162:163], v[162:163], 0, v[160:161]
	global_load_dwordx4 v[184:187], v[162:163], off
	global_load_dwordx4 v[188:191], v[162:163], off offset:256
	v_add_co_u32_e32 v242, vcc, s94, v162
	v_addc_co_u32_e32 v243, vcc, 0, v163, vcc
	global_load_dwordx4 v[192:195], v[242:243], off
	global_load_dwordx4 v[196:199], v[242:243], off offset:256
	v_add_co_u32_e32 v242, vcc, s73, v162
	v_addc_co_u32_e32 v243, vcc, 0, v163, vcc
	global_load_dwordx4 v[200:203], v[242:243], off
	global_load_dwordx4 v[222:225], v[242:243], off offset:256
	v_add_co_u32_e32 v242, vcc, s93, v162
	v_addc_co_u32_e32 v243, vcc, 0, v163, vcc
	global_load_dwordx4 v[226:229], v[242:243], off
	global_load_dwordx4 v[230:233], v[242:243], off offset:256
	v_add_co_u32_e32 v242, vcc, s49, v162
	v_addc_co_u32_e32 v243, vcc, 0, v163, vcc
	global_load_dwordx4 v[234:237], v[242:243], off
	global_load_dwordx4 v[238:241], v[242:243], off offset:256
	v_lshl_add_u64 v[166:167], s[10:11], 0, v[166:167]
	v_lshl_add_u64 v[160:161], v[166:167], 0, v[160:161]
	v_readlane_b32 s90, v254, 50
	s_mov_b64 s[42:43], -1
	v_readlane_b32 s91, v254, 51
	s_waitcnt vmcnt(9)
	v_mov_b32_e32 v180, v184
	v_mov_b32_e32 v181, v185
	v_mov_b32_e32 v182, v186
	v_mov_b32_e32 v183, v187
	v_add_co_u32_e32 v242, vcc, s50, v162
	v_addc_co_u32_e32 v243, vcc, 0, v163, vcc
	global_load_dwordx4 v[184:187], v[242:243], off
	v_pk_add_f32 v[142:143], v[142:143], v[36:37]
	v_pk_add_f32 v[146:147], v[146:147], v[40:41]
	v_pk_add_f32 v[144:145], v[144:145], v[38:39]
	v_pk_add_f32 v[140:141], v[140:141], v[34:35]
	v_pk_mul_f32 v[144:145], v[144:145], s[74:75] op_sel_hi:[1,0]
	v_pk_mul_f32 v[146:147], v[146:147], s[74:75] op_sel_hi:[1,0]
	v_pk_mul_f32 v[140:141], v[140:141], s[74:75] op_sel_hi:[1,0]
	v_pk_mul_f32 v[142:143], v[142:143], s[74:75] op_sel_hi:[1,0]
	v_exp_f32_e32 v144, v144
	v_exp_f32_e32 v145, v145
	v_exp_f32_e32 v146, v146
	v_exp_f32_e32 v147, v147
	v_exp_f32_e32 v140, v140
	v_exp_f32_e32 v141, v141
	v_exp_f32_e32 v142, v142
	v_exp_f32_e32 v143, v143
	v_pk_add_f32 v[144:145], v[144:145], 1.0 op_sel_hi:[1,0]
	v_pk_add_f32 v[146:147], v[146:147], 1.0 op_sel_hi:[1,0]
	v_pk_add_f32 v[140:141], v[140:141], 1.0 op_sel_hi:[1,0]
	v_pk_add_f32 v[142:143], v[142:143], 1.0 op_sel_hi:[1,0]
	v_rcp_f32_e32 v144, v144
	v_rcp_f32_e32 v145, v145
	v_rcp_f32_e32 v146, v146
	v_rcp_f32_e32 v147, v147
	v_rcp_f32_e32 v140, v140
	v_rcp_f32_e32 v141, v141
	v_rcp_f32_e32 v142, v142
	v_rcp_f32_e32 v143, v143
	v_lshlrev_b32_e32 v166, 16, v180
	v_and_b32_e32 v167, 0xffff0000, v180
	v_lshlrev_b32_e32 v168, 16, v181
	v_and_b32_e32 v169, 0xffff0000, v181
	v_lshlrev_b32_e32 v172, 16, v182
	v_and_b32_e32 v173, 0xffff0000, v182
	v_lshlrev_b32_e32 v180, 16, v183
	v_and_b32_e32 v181, 0xffff0000, v183
	v_pk_mul_f32 v[146:147], v[146:147], v[168:169]
	v_pk_mul_f32 v[144:145], v[144:145], v[166:167]
	v_pk_mul_f32 v[166:167], v[142:143], v[180:181]
	v_pk_mul_f32 v[142:143], v[140:141], v[172:173]
	v_cvt_pk_bf16_f32 v140, v144, v145
	v_cvt_pk_bf16_f32 v141, v146, v147
	v_cvt_pk_bf16_f32 v142, v142, v143
	v_cvt_pk_bf16_f32 v143, v166, v167
	global_store_dwordx4 v[160:161], v[140:143], off
	v_pk_add_f32 v[138:139], v[138:139], v[24:25]
	v_pk_add_f32 v[136:137], v[136:137], v[22:23]
	v_pk_add_f32 v[134:135], v[134:135], v[16:17]
	v_pk_add_f32 v[132:133], v[132:133], v[14:15]
	v_pk_mul_f32 v[136:137], v[136:137], s[74:75] op_sel_hi:[1,0]
	v_pk_mul_f32 v[138:139], v[138:139], s[74:75] op_sel_hi:[1,0]
	v_pk_mul_f32 v[132:133], v[132:133], s[74:75] op_sel_hi:[1,0]
	v_pk_mul_f32 v[134:135], v[134:135], s[74:75] op_sel_hi:[1,0]
	v_exp_f32_e32 v136, v136
	v_exp_f32_e32 v137, v137
	v_exp_f32_e32 v138, v138
	v_exp_f32_e32 v139, v139
	v_exp_f32_e32 v132, v132
	v_exp_f32_e32 v133, v133
	v_exp_f32_e32 v134, v134
	v_exp_f32_e32 v135, v135
	v_pk_add_f32 v[136:137], v[136:137], 1.0 op_sel_hi:[1,0]
	v_pk_add_f32 v[138:139], v[138:139], 1.0 op_sel_hi:[1,0]
	v_pk_add_f32 v[132:133], v[132:133], 1.0 op_sel_hi:[1,0]
	v_pk_add_f32 v[134:135], v[134:135], 1.0 op_sel_hi:[1,0]
	v_rcp_f32_e32 v136, v136
	v_rcp_f32_e32 v137, v137
	v_rcp_f32_e32 v138, v138
	v_rcp_f32_e32 v139, v139
	v_rcp_f32_e32 v132, v132
	v_rcp_f32_e32 v133, v133
	v_rcp_f32_e32 v134, v134
	v_rcp_f32_e32 v135, v135
	v_pk_add_f32 v[128:129], v[128:129], v[38:39]
	v_pk_add_f32 v[124:125], v[124:125], v[34:35]
	v_pk_add_f32 v[130:131], v[130:131], v[40:41]
	v_pk_mul_f32 v[128:129], v[128:129], s[74:75] op_sel_hi:[1,0]
	v_pk_add_f32 v[126:127], v[126:127], v[36:37]
	v_pk_mul_f32 v[124:125], v[124:125], s[74:75] op_sel_hi:[1,0]
	v_pk_mul_f32 v[130:131], v[130:131], s[74:75] op_sel_hi:[1,0]
	v_exp_f32_e32 v128, v128
	v_exp_f32_e32 v129, v129
	v_pk_mul_f32 v[126:127], v[126:127], s[74:75] op_sel_hi:[1,0]
	v_exp_f32_e32 v124, v124
	v_exp_f32_e32 v125, v125
	v_exp_f32_e32 v130, v130
	v_exp_f32_e32 v131, v131
	v_exp_f32_e32 v126, v126
	v_exp_f32_e32 v127, v127
	v_pk_add_f32 v[128:129], v[128:129], 1.0 op_sel_hi:[1,0]
	v_pk_add_f32 v[124:125], v[124:125], 1.0 op_sel_hi:[1,0]
	v_pk_add_f32 v[130:131], v[130:131], 1.0 op_sel_hi:[1,0]
	v_rcp_f32_e32 v128, v128
	v_rcp_f32_e32 v129, v129
	v_pk_add_f32 v[126:127], v[126:127], 1.0 op_sel_hi:[1,0]
	v_rcp_f32_e32 v124, v124
	v_rcp_f32_e32 v125, v125
	v_rcp_f32_e32 v130, v130
	v_rcp_f32_e32 v131, v131
	v_rcp_f32_e32 v126, v126
	v_rcp_f32_e32 v127, v127
	v_pk_add_f32 v[122:123], v[122:123], v[24:25]
	v_pk_add_f32 v[120:121], v[120:121], v[22:23]
	v_pk_add_f32 v[118:119], v[118:119], v[16:17]
	v_pk_add_f32 v[116:117], v[116:117], v[14:15]
	v_pk_mul_f32 v[120:121], v[120:121], s[74:75] op_sel_hi:[1,0]
	v_pk_mul_f32 v[122:123], v[122:123], s[74:75] op_sel_hi:[1,0]
	v_pk_mul_f32 v[116:117], v[116:117], s[74:75] op_sel_hi:[1,0]
	v_pk_mul_f32 v[118:119], v[118:119], s[74:75] op_sel_hi:[1,0]
	v_exp_f32_e32 v120, v120
	v_exp_f32_e32 v121, v121
	v_exp_f32_e32 v122, v122
	v_exp_f32_e32 v123, v123
	v_exp_f32_e32 v116, v116
	v_exp_f32_e32 v117, v117
	v_exp_f32_e32 v118, v118
	v_exp_f32_e32 v119, v119
	v_pk_add_f32 v[120:121], v[120:121], 1.0 op_sel_hi:[1,0]
	v_pk_add_f32 v[122:123], v[122:123], 1.0 op_sel_hi:[1,0]
	v_pk_add_f32 v[116:117], v[116:117], 1.0 op_sel_hi:[1,0]
	v_pk_add_f32 v[118:119], v[118:119], 1.0 op_sel_hi:[1,0]
	v_rcp_f32_e32 v120, v120
	v_rcp_f32_e32 v121, v121
	v_rcp_f32_e32 v122, v122
	s_waitcnt vmcnt(10)
; #define GAS __attribute__((address_space(1)))
; __device__ __forceinline__ u32x4 pack8(f32x4 v0, f32x4 v1) { u32x4 w; w.x = cvt_pk_bf16(v0[0], v0[1]); w.y = cvt_pk_bf16(v0[2], v0[3]); w.z = cvt_pk_bf16(v1[0], v1[1]); w.w = cvt_pk_bf16(v1[2], v1[3]); return w; }
; __device__ __forceinline__ void unpack8(u32x4 w, f32x4& v0, f32x4& v1) { v0 = (f32x4){bflo(w.x), bfhi(w.x), bflo(w.y), bfhi(w.y)}; v1 = (f32x4){bflo(w.z), bfhi(w.z), bflo(w.w), bfhi(w.w)}; }
; #define GAS __attribute__((address_space(1)))
; __device__ __forceinline__ f32x4 sigmoid4(f32x4 v) {
;     const f32x2 t0 = (f32x2){v[0], v[1]} * -1.4426950408889634f, t1 = (f32x2){v[2], v[3]} * -1.4426950408889634f;
;     const f32x2 d0 = (f32x2){__builtin_amdgcn_exp2f(t0.x), __builtin_amdgcn_exp2f(t0.y)} + 1.0f, d1 = (f32x2){__builtin_amdgcn_exp2f(t1.x), __builtin_amdgcn_exp2f(t1.y)} + 1.0f;
;     return (f32x4){__builtin_amdgcn_rcpf(d0.x), __builtin_amdgcn_rcpf(d0.y), __builtin_amdgcn_rcpf(d1.x), __builtin_amdgcn_rcpf(d1.y)}; }
;     __device__ __forceinline__ void operator()(const f32x4 (&acc)[2][2][4][2], const Unit& u, int wr, int wc, int fr, int fq) const {
;     ...
; #pragma unroll
;         for (int ai = 0; ai < 2; ++ai)
; #pragma unroll
;             for (int m = 0; m < 4; ++m) { const size_t off = (size_t)(ai * HALF + m * 16) * 1024;
; #pragma unroll
;                 for (int bj = 0; bj < 2; ++bj) { f32x4 z0, z1; unpack8(*(const GAS u32x4*)(zb + off + bj * HALF), z0, z1);
;                     const f32x4 v0 = z0 * sigmoid4(acc[ai][bj][m][0] + bv[bj][0]), v1 = z1 * sigmoid4(acc[ai][bj][m][1] + bv[bj][1]);
;                     *(GAS u32x4*)(sob + off + bj * HALF) = pack8(v0, v1); } }
	v_mov_b32_e32 v140, v188
	v_mov_b32_e32 v141, v189
	v_mov_b32_e32 v142, v190
	v_mov_b32_e32 v143, v191
	global_load_dwordx4 v[188:191], v[242:243], off offset:256
	v_lshlrev_b32_e32 v144, 16, v140
	v_and_b32_e32 v145, 0xffff0000, v140
	v_lshlrev_b32_e32 v140, 16, v141
	v_and_b32_e32 v141, 0xffff0000, v141
	v_lshlrev_b32_e32 v146, 16, v142
	v_and_b32_e32 v147, 0xffff0000, v142
	v_lshlrev_b32_e32 v142, 16, v143
	v_and_b32_e32 v143, 0xffff0000, v143
	v_pk_mul_f32 v[138:139], v[138:139], v[140:141]
	v_pk_mul_f32 v[136:137], v[136:137], v[144:145]
	v_pk_mul_f32 v[140:141], v[134:135], v[142:143]
	v_pk_mul_f32 v[134:135], v[132:133], v[146:147]
	v_cvt_pk_bf16_f32 v132, v136, v137
	v_cvt_pk_bf16_f32 v133, v138, v139
	v_cvt_pk_bf16_f32 v134, v134, v135
	v_cvt_pk_bf16_f32 v135, v140, v141
	global_store_dwordx4 v[160:161], v[132:135], off offset:256
	v_rcp_f32_e32 v123, v123
	v_rcp_f32_e32 v116, v116
	v_add_co_u32_e32 v132, vcc, s94, v162
	v_rcp_f32_e32 v117, v117
	s_nop 0
	v_addc_co_u32_e32 v133, vcc, 0, v163, vcc
	v_rcp_f32_e32 v118, v118
	v_rcp_f32_e32 v119, v119
	v_pk_add_f32 v[112:113], v[112:113], v[38:39]
	v_pk_add_f32 v[108:109], v[108:109], v[34:35]
	v_pk_add_f32 v[114:115], v[114:115], v[40:41]
	v_pk_mul_f32 v[112:113], v[112:113], s[74:75] op_sel_hi:[1,0]
	v_pk_add_f32 v[110:111], v[110:111], v[36:37]
	v_pk_mul_f32 v[108:109], v[108:109], s[74:75] op_sel_hi:[1,0]
	v_pk_mul_f32 v[114:115], v[114:115], s[74:75] op_sel_hi:[1,0]
	v_exp_f32_e32 v112, v112
	v_exp_f32_e32 v113, v113
	v_pk_mul_f32 v[110:111], v[110:111], s[74:75] op_sel_hi:[1,0]
	v_exp_f32_e32 v108, v108
	v_exp_f32_e32 v109, v109
	v_exp_f32_e32 v114, v114
	v_exp_f32_e32 v115, v115
	v_exp_f32_e32 v110, v110
	v_exp_f32_e32 v111, v111
	v_pk_add_f32 v[112:113], v[112:113], 1.0 op_sel_hi:[1,0]
	v_pk_add_f32 v[108:109], v[108:109], 1.0 op_sel_hi:[1,0]
	v_pk_add_f32 v[114:115], v[114:115], 1.0 op_sel_hi:[1,0]
	v_rcp_f32_e32 v112, v112
	v_rcp_f32_e32 v113, v113
	v_pk_add_f32 v[110:111], v[110:111], 1.0 op_sel_hi:[1,0]
	v_rcp_f32_e32 v108, v108
	v_rcp_f32_e32 v109, v109
	v_rcp_f32_e32 v114, v114
	v_rcp_f32_e32 v115, v115
	v_rcp_f32_e32 v110, v110
	v_rcp_f32_e32 v111, v111
	v_pk_add_f32 v[106:107], v[106:107], v[24:25]
	v_pk_add_f32 v[104:105], v[104:105], v[22:23]
	v_pk_add_f32 v[102:103], v[102:103], v[16:17]
	v_pk_add_f32 v[100:101], v[100:101], v[14:15]
	v_pk_mul_f32 v[104:105], v[104:105], s[74:75] op_sel_hi:[1,0]
	v_pk_mul_f32 v[106:107], v[106:107], s[74:75] op_sel_hi:[1,0]
	v_pk_mul_f32 v[100:101], v[100:101], s[74:75] op_sel_hi:[1,0]
	v_pk_mul_f32 v[102:103], v[102:103], s[74:75] op_sel_hi:[1,0]
	v_exp_f32_e32 v104, v104
	v_exp_f32_e32 v105, v105
	v_exp_f32_e32 v106, v106
	v_exp_f32_e32 v107, v107
	v_exp_f32_e32 v100, v100
	v_exp_f32_e32 v101, v101
	v_exp_f32_e32 v102, v102
	v_exp_f32_e32 v103, v103
	v_pk_add_f32 v[104:105], v[104:105], 1.0 op_sel_hi:[1,0]
	v_pk_add_f32 v[106:107], v[106:107], 1.0 op_sel_hi:[1,0]
	v_pk_add_f32 v[100:101], v[100:101], 1.0 op_sel_hi:[1,0]
	v_pk_add_f32 v[102:103], v[102:103], 1.0 op_sel_hi:[1,0]
	v_rcp_f32_e32 v104, v104
	v_rcp_f32_e32 v105, v105
	v_rcp_f32_e32 v106, v106
	v_rcp_f32_e32 v107, v107
	v_rcp_f32_e32 v100, v100
	v_rcp_f32_e32 v101, v101
	v_rcp_f32_e32 v102, v102
	v_rcp_f32_e32 v103, v103
	v_pk_add_f32 v[94:95], v[94:95], v[38:39]
	v_pk_add_f32 v[90:91], v[90:91], v[34:35]
	v_pk_add_f32 v[96:97], v[96:97], v[40:41]
	v_pk_mul_f32 v[94:95], v[94:95], s[74:75] op_sel_hi:[1,0]
	v_pk_add_f32 v[92:93], v[92:93], v[36:37]
	v_pk_mul_f32 v[90:91], v[90:91], s[74:75] op_sel_hi:[1,0]
	v_pk_mul_f32 v[96:97], v[96:97], s[74:75] op_sel_hi:[1,0]
	v_exp_f32_e32 v94, v94
	v_exp_f32_e32 v95, v95
	v_pk_mul_f32 v[92:93], v[92:93], s[74:75] op_sel_hi:[1,0]
	v_exp_f32_e32 v90, v90
	v_exp_f32_e32 v91, v91
	v_exp_f32_e32 v96, v96
	v_exp_f32_e32 v97, v97
	v_exp_f32_e32 v92, v92
	v_exp_f32_e32 v93, v93
	v_pk_add_f32 v[94:95], v[94:95], 1.0 op_sel_hi:[1,0]
	v_pk_add_f32 v[90:91], v[90:91], 1.0 op_sel_hi:[1,0]
	v_pk_add_f32 v[96:97], v[96:97], 1.0 op_sel_hi:[1,0]
	v_rcp_f32_e32 v94, v94
	v_rcp_f32_e32 v95, v95
	s_waitcnt vmcnt(11)
	v_mov_b32_e32 v134, v192
	v_mov_b32_e32 v135, v193
	v_mov_b32_e32 v136, v194
	v_mov_b32_e32 v137, v195
	v_add_co_u32_e32 v242, vcc, s51, v162
	v_addc_co_u32_e32 v243, vcc, 0, v163, vcc
	global_load_dwordx4 v[192:195], v[242:243], off
	v_lshlrev_b32_e32 v138, 16, v134
	v_and_b32_e32 v139, 0xffff0000, v134
	v_lshlrev_b32_e32 v140, 16, v136
	v_and_b32_e32 v141, 0xffff0000, v136
	v_lshlrev_b32_e32 v134, 16, v135
	v_and_b32_e32 v135, 0xffff0000, v135
	v_lshlrev_b32_e32 v136, 16, v137
	v_and_b32_e32 v137, 0xffff0000, v137
	v_pk_mul_f32 v[128:129], v[128:129], v[138:139]
	v_pk_mul_f32 v[124:125], v[124:125], v[140:141]
	v_pk_mul_f32 v[130:131], v[130:131], v[134:135]
	v_pk_mul_f32 v[134:135], v[126:127], v[136:137]
	v_cvt_pk_bf16_f32 v126, v128, v129
	v_cvt_pk_bf16_f32 v128, v124, v125
	v_add_co_u32_e32 v124, vcc, s94, v160
	v_cvt_pk_bf16_f32 v127, v130, v131
	v_cvt_pk_bf16_f32 v129, v134, v135
	v_addc_co_u32_e32 v125, vcc, 0, v161, vcc
	global_store_dwordx4 v[124:125], v[126:129], off
	v_pk_add_f32 v[92:93], v[92:93], 1.0 op_sel_hi:[1,0]
	v_rcp_f32_e32 v90, v90
	v_rcp_f32_e32 v91, v91
	v_rcp_f32_e32 v96, v96
	v_rcp_f32_e32 v97, v97
	v_rcp_f32_e32 v92, v92
	v_rcp_f32_e32 v93, v93
	v_pk_add_f32 v[88:89], v[88:89], v[24:25]
	v_pk_add_f32 v[86:87], v[86:87], v[22:23]
	v_pk_add_f32 v[84:85], v[84:85], v[16:17]
	v_pk_add_f32 v[82:83], v[82:83], v[14:15]
	v_pk_mul_f32 v[86:87], v[86:87], s[74:75] op_sel_hi:[1,0]
	v_pk_mul_f32 v[88:89], v[88:89], s[74:75] op_sel_hi:[1,0]
	v_pk_mul_f32 v[82:83], v[82:83], s[74:75] op_sel_hi:[1,0]
; #define GAS __attribute__((address_space(1)))
; __device__ __forceinline__ u32x4 pack8(f32x4 v0, f32x4 v1) { u32x4 w; w.x = cvt_pk_bf16(v0[0], v0[1]); w.y = cvt_pk_bf16(v0[2], v0[3]); w.z = cvt_pk_bf16(v1[0], v1[1]); w.w = cvt_pk_bf16(v1[2], v1[3]); return w; }
; __device__ __forceinline__ void unpack8(u32x4 w, f32x4& v0, f32x4& v1) { v0 = (f32x4){bflo(w.x), bfhi(w.x), bflo(w.y), bfhi(w.y)}; v1 = (f32x4){bflo(w.z), bfhi(w.z), bflo(w.w), bfhi(w.w)}; }
; #define GAS __attribute__((address_space(1)))
; __device__ __forceinline__ f32x4 sigmoid4(f32x4 v) {
;     const f32x2 t0 = (f32x2){v[0], v[1]} * -1.4426950408889634f, t1 = (f32x2){v[2], v[3]} * -1.4426950408889634f;
;     const f32x2 d0 = (f32x2){__builtin_amdgcn_exp2f(t0.x), __builtin_amdgcn_exp2f(t0.y)} + 1.0f, d1 = (f32x2){__builtin_amdgcn_exp2f(t1.x), __builtin_amdgcn_exp2f(t1.y)} + 1.0f;
;     return (f32x4){__builtin_amdgcn_rcpf(d0.x), __builtin_amdgcn_rcpf(d0.y), __builtin_amdgcn_rcpf(d1.x), __builtin_amdgcn_rcpf(d1.y)}; }
;     __device__ __forceinline__ void operator()(const f32x4 (&acc)[2][2][4][2], const Unit& u, int wr, int wc, int fr, int fq) const {
;     ...
; #pragma unroll
;         for (int ai = 0; ai < 2; ++ai)
; #pragma unroll
;             for (int m = 0; m < 4; ++m) { const size_t off = (size_t)(ai * HALF + m * 16) * 1024;
; #pragma unroll
;                 for (int bj = 0; bj < 2; ++bj) { f32x4 z0, z1; unpack8(*(const GAS u32x4*)(zb + off + bj * HALF), z0, z1);
;                     const f32x4 v0 = z0 * sigmoid4(acc[ai][bj][m][0] + bv[bj][0]), v1 = z1 * sigmoid4(acc[ai][bj][m][1] + bv[bj][1]);
;                     *(GAS u32x4*)(sob + off + bj * HALF) = pack8(v0, v1); } }
	v_pk_mul_f32 v[84:85], v[84:85], s[74:75] op_sel_hi:[1,0]
	v_exp_f32_e32 v86, v86
	v_exp_f32_e32 v87, v87
	v_exp_f32_e32 v88, v88
	v_exp_f32_e32 v89, v89
	v_exp_f32_e32 v82, v82
	v_exp_f32_e32 v83, v83
	v_exp_f32_e32 v84, v84
	v_exp_f32_e32 v85, v85
	v_pk_add_f32 v[86:87], v[86:87], 1.0 op_sel_hi:[1,0]
	v_pk_add_f32 v[88:89], v[88:89], 1.0 op_sel_hi:[1,0]
	v_pk_add_f32 v[82:83], v[82:83], 1.0 op_sel_hi:[1,0]
	v_pk_add_f32 v[84:85], v[84:85], 1.0 op_sel_hi:[1,0]
	v_rcp_f32_e32 v86, v86
	v_rcp_f32_e32 v87, v87
	v_rcp_f32_e32 v88, v88
	v_rcp_f32_e32 v89, v89
	v_rcp_f32_e32 v82, v82
	v_rcp_f32_e32 v83, v83
	v_rcp_f32_e32 v84, v84
	v_rcp_f32_e32 v85, v85
	v_pk_add_f32 v[78:79], v[78:79], v[38:39]
	v_pk_add_f32 v[74:75], v[74:75], v[34:35]
	v_pk_add_f32 v[80:81], v[80:81], v[40:41]
	v_pk_mul_f32 v[78:79], v[78:79], s[74:75] op_sel_hi:[1,0]
	v_pk_add_f32 v[76:77], v[76:77], v[36:37]
	v_pk_mul_f32 v[74:75], v[74:75], s[74:75] op_sel_hi:[1,0]
	v_pk_mul_f32 v[80:81], v[80:81], s[74:75] op_sel_hi:[1,0]
	v_exp_f32_e32 v78, v78
	v_exp_f32_e32 v79, v79
	v_pk_mul_f32 v[76:77], v[76:77], s[74:75] op_sel_hi:[1,0]
	v_exp_f32_e32 v74, v74
	v_exp_f32_e32 v75, v75
	v_exp_f32_e32 v80, v80
	v_exp_f32_e32 v81, v81
	v_exp_f32_e32 v76, v76
	v_exp_f32_e32 v77, v77
	v_pk_add_f32 v[78:79], v[78:79], 1.0 op_sel_hi:[1,0]
	v_pk_add_f32 v[74:75], v[74:75], 1.0 op_sel_hi:[1,0]
	v_pk_add_f32 v[80:81], v[80:81], 1.0 op_sel_hi:[1,0]
	v_rcp_f32_e32 v78, v78
	v_rcp_f32_e32 v79, v79
	v_pk_add_f32 v[76:77], v[76:77], 1.0 op_sel_hi:[1,0]
	v_rcp_f32_e32 v74, v74
	v_rcp_f32_e32 v75, v75
	v_rcp_f32_e32 v80, v80
	v_rcp_f32_e32 v81, v81
	v_rcp_f32_e32 v76, v76
	v_rcp_f32_e32 v77, v77
	v_pk_add_f32 v[72:73], v[72:73], v[24:25]
	v_pk_add_f32 v[70:71], v[70:71], v[22:23]
	v_pk_add_f32 v[68:69], v[68:69], v[16:17]
	v_pk_add_f32 v[66:67], v[66:67], v[14:15]
	v_pk_mul_f32 v[70:71], v[70:71], s[74:75] op_sel_hi:[1,0]
	v_pk_mul_f32 v[72:73], v[72:73], s[74:75] op_sel_hi:[1,0]
	v_pk_mul_f32 v[66:67], v[66:67], s[74:75] op_sel_hi:[1,0]
	v_pk_mul_f32 v[68:69], v[68:69], s[74:75] op_sel_hi:[1,0]
	v_exp_f32_e32 v70, v70
	v_exp_f32_e32 v71, v71
	v_exp_f32_e32 v72, v72
	v_exp_f32_e32 v73, v73
	v_exp_f32_e32 v66, v66
	v_exp_f32_e32 v67, v67
	v_exp_f32_e32 v68, v68
	v_exp_f32_e32 v69, v69
	s_waitcnt vmcnt(12)
	v_mov_b32_e32 v126, v196
	v_mov_b32_e32 v127, v197
	v_mov_b32_e32 v128, v198
	v_mov_b32_e32 v129, v199
	global_load_dwordx4 v[196:199], v[242:243], off offset:256
	v_lshlrev_b32_e32 v130, 16, v126
	v_and_b32_e32 v131, 0xffff0000, v126
	v_lshlrev_b32_e32 v126, 16, v127
	v_and_b32_e32 v127, 0xffff0000, v127
	v_lshlrev_b32_e32 v132, 16, v128
	v_and_b32_e32 v133, 0xffff0000, v128
	v_lshlrev_b32_e32 v128, 16, v129
	v_and_b32_e32 v129, 0xffff0000, v129
	v_pk_mul_f32 v[122:123], v[122:123], v[126:127]
	v_pk_mul_f32 v[120:121], v[120:121], v[130:131]
	v_pk_mul_f32 v[126:127], v[118:119], v[128:129]
	v_pk_mul_f32 v[118:119], v[116:117], v[132:133]
	v_cvt_pk_bf16_f32 v116, v120, v121
	v_cvt_pk_bf16_f32 v117, v122, v123
	v_cvt_pk_bf16_f32 v118, v118, v119
	v_cvt_pk_bf16_f32 v119, v126, v127
	global_store_dwordx4 v[124:125], v[116:119], off offset:256
	v_pk_add_f32 v[70:71], v[70:71], 1.0 op_sel_hi:[1,0]
	v_pk_add_f32 v[72:73], v[72:73], 1.0 op_sel_hi:[1,0]
	v_add_co_u32_e32 v116, vcc, s73, v162
	v_pk_add_f32 v[66:67], v[66:67], 1.0 op_sel_hi:[1,0]
	s_nop 0
	v_addc_co_u32_e32 v117, vcc, 0, v163, vcc
	v_pk_add_f32 v[68:69], v[68:69], 1.0 op_sel_hi:[1,0]
	v_rcp_f32_e32 v70, v70
	v_rcp_f32_e32 v71, v71
	v_rcp_f32_e32 v72, v72
	v_rcp_f32_e32 v73, v73
	v_rcp_f32_e32 v66, v66
	v_rcp_f32_e32 v67, v67
	v_rcp_f32_e32 v68, v68
	v_rcp_f32_e32 v69, v69
	v_pk_add_f32 v[62:63], v[62:63], v[38:39]
	v_pk_add_f32 v[58:59], v[58:59], v[34:35]
	v_pk_add_f32 v[64:65], v[64:65], v[40:41]
	v_pk_mul_f32 v[62:63], v[62:63], s[74:75] op_sel_hi:[1,0]
	v_pk_add_f32 v[60:61], v[60:61], v[36:37]
	v_pk_mul_f32 v[58:59], v[58:59], s[74:75] op_sel_hi:[1,0]
	v_pk_mul_f32 v[64:65], v[64:65], s[74:75] op_sel_hi:[1,0]
	v_exp_f32_e32 v62, v62
	v_exp_f32_e32 v63, v63
	v_pk_mul_f32 v[60:61], v[60:61], s[74:75] op_sel_hi:[1,0]
	v_exp_f32_e32 v58, v58
	v_exp_f32_e32 v59, v59
	v_exp_f32_e32 v64, v64
	v_exp_f32_e32 v65, v65
	v_exp_f32_e32 v60, v60
	v_exp_f32_e32 v61, v61
	v_pk_add_f32 v[62:63], v[62:63], 1.0 op_sel_hi:[1,0]
	v_pk_add_f32 v[58:59], v[58:59], 1.0 op_sel_hi:[1,0]
	v_pk_add_f32 v[64:65], v[64:65], 1.0 op_sel_hi:[1,0]
	v_rcp_f32_e32 v62, v62
	v_rcp_f32_e32 v63, v63
	v_pk_add_f32 v[60:61], v[60:61], 1.0 op_sel_hi:[1,0]
	v_rcp_f32_e32 v58, v58
	v_rcp_f32_e32 v59, v59
	v_rcp_f32_e32 v64, v64
	v_rcp_f32_e32 v65, v65
	v_rcp_f32_e32 v60, v60
	v_rcp_f32_e32 v61, v61
	v_pk_add_f32 v[56:57], v[56:57], v[24:25]
	v_pk_add_f32 v[54:55], v[54:55], v[22:23]
	v_pk_add_f32 v[52:53], v[52:53], v[16:17]
	v_pk_add_f32 v[50:51], v[50:51], v[14:15]
	v_pk_mul_f32 v[54:55], v[54:55], s[74:75] op_sel_hi:[1,0]
	v_pk_mul_f32 v[56:57], v[56:57], s[74:75] op_sel_hi:[1,0]
	v_pk_mul_f32 v[50:51], v[50:51], s[74:75] op_sel_hi:[1,0]
	v_pk_mul_f32 v[52:53], v[52:53], s[74:75] op_sel_hi:[1,0]
	v_exp_f32_e32 v54, v54
	v_exp_f32_e32 v55, v55
	v_exp_f32_e32 v56, v56
	v_exp_f32_e32 v57, v57
	v_exp_f32_e32 v50, v50
	v_exp_f32_e32 v51, v51
	v_exp_f32_e32 v52, v52
	v_exp_f32_e32 v53, v53
	v_pk_add_f32 v[54:55], v[54:55], 1.0 op_sel_hi:[1,0]
	v_pk_add_f32 v[56:57], v[56:57], 1.0 op_sel_hi:[1,0]
	v_pk_add_f32 v[50:51], v[50:51], 1.0 op_sel_hi:[1,0]
	v_pk_add_f32 v[52:53], v[52:53], 1.0 op_sel_hi:[1,0]
	v_rcp_f32_e32 v54, v54
	v_rcp_f32_e32 v55, v55
	v_rcp_f32_e32 v56, v56
	v_rcp_f32_e32 v57, v57
	v_rcp_f32_e32 v50, v50
	v_rcp_f32_e32 v51, v51
	v_rcp_f32_e32 v52, v52
	v_rcp_f32_e32 v53, v53
	v_pk_add_f32 v[46:47], v[46:47], v[38:39]
	v_pk_add_f32 v[42:43], v[42:43], v[34:35]
	v_pk_add_f32 v[48:49], v[48:49], v[40:41]
	v_pk_mul_f32 v[46:47], v[46:47], s[74:75] op_sel_hi:[1,0]
	v_pk_add_f32 v[44:45], v[44:45], v[36:37]
	v_pk_mul_f32 v[42:43], v[42:43], s[74:75] op_sel_hi:[1,0]
	v_pk_mul_f32 v[48:49], v[48:49], s[74:75] op_sel_hi:[1,0]
	v_exp_f32_e32 v46, v46
	v_exp_f32_e32 v47, v47
	v_pk_mul_f32 v[44:45], v[44:45], s[74:75] op_sel_hi:[1,0]
	v_exp_f32_e32 v42, v42
	v_exp_f32_e32 v43, v43
	v_exp_f32_e32 v48, v48
	v_exp_f32_e32 v49, v49
	s_waitcnt vmcnt(13)
; #define GAS __attribute__((address_space(1)))
; __device__ __forceinline__ u32x4 pack8(f32x4 v0, f32x4 v1) { u32x4 w; w.x = cvt_pk_bf16(v0[0], v0[1]); w.y = cvt_pk_bf16(v0[2], v0[3]); w.z = cvt_pk_bf16(v1[0], v1[1]); w.w = cvt_pk_bf16(v1[2], v1[3]); return w; }
; __device__ __forceinline__ void unpack8(u32x4 w, f32x4& v0, f32x4& v1) { v0 = (f32x4){bflo(w.x), bfhi(w.x), bflo(w.y), bfhi(w.y)}; v1 = (f32x4){bflo(w.z), bfhi(w.z), bflo(w.w), bfhi(w.w)}; }
; #define GAS __attribute__((address_space(1)))
; __device__ __forceinline__ f32x4 sigmoid4(f32x4 v) {
;     const f32x2 t0 = (f32x2){v[0], v[1]} * -1.4426950408889634f, t1 = (f32x2){v[2], v[3]} * -1.4426950408889634f;
;     const f32x2 d0 = (f32x2){__builtin_amdgcn_exp2f(t0.x), __builtin_amdgcn_exp2f(t0.y)} + 1.0f, d1 = (f32x2){__builtin_amdgcn_exp2f(t1.x), __builtin_amdgcn_exp2f(t1.y)} + 1.0f;
;     return (f32x4){__builtin_amdgcn_rcpf(d0.x), __builtin_amdgcn_rcpf(d0.y), __builtin_amdgcn_rcpf(d1.x), __builtin_amdgcn_rcpf(d1.y)}; }
;     __device__ __forceinline__ void operator()(const f32x4 (&acc)[2][2][4][2], const Unit& u, int wr, int wc, int fr, int fq) const {
;     ...
; #pragma unroll
;         for (int ai = 0; ai < 2; ++ai)
; #pragma unroll
;             for (int m = 0; m < 4; ++m) { const size_t off = (size_t)(ai * HALF + m * 16) * 1024;
; #pragma unroll
;                 for (int bj = 0; bj < 2; ++bj) { f32x4 z0, z1; unpack8(*(const GAS u32x4*)(zb + off + bj * HALF), z0, z1);
;                     const f32x4 v0 = z0 * sigmoid4(acc[ai][bj][m][0] + bv[bj][0]), v1 = z1 * sigmoid4(acc[ai][bj][m][1] + bv[bj][1]);
;                     *(GAS u32x4*)(sob + off + bj * HALF) = pack8(v0, v1); } }
	v_mov_b32_e32 v118, v200
	v_mov_b32_e32 v119, v201
	v_mov_b32_e32 v120, v202
	v_mov_b32_e32 v121, v203
	v_add_co_u32_e32 v242, vcc, s66, v162
	v_addc_co_u32_e32 v243, vcc, 0, v163, vcc
	global_load_dwordx4 v[200:203], v[242:243], off
	v_lshlrev_b32_e32 v122, 16, v118
	v_and_b32_e32 v123, 0xffff0000, v118
	v_lshlrev_b32_e32 v124, 16, v120
	v_and_b32_e32 v125, 0xffff0000, v120
	v_lshlrev_b32_e32 v118, 16, v119
	v_and_b32_e32 v119, 0xffff0000, v119
	v_lshlrev_b32_e32 v120, 16, v121
	v_and_b32_e32 v121, 0xffff0000, v121
	v_pk_mul_f32 v[112:113], v[112:113], v[122:123]
	v_pk_mul_f32 v[108:109], v[108:109], v[124:125]
	v_pk_mul_f32 v[114:115], v[114:115], v[118:119]
	v_pk_mul_f32 v[118:119], v[110:111], v[120:121]
	v_cvt_pk_bf16_f32 v110, v112, v113
	v_cvt_pk_bf16_f32 v112, v108, v109
	v_add_co_u32_e32 v108, vcc, s73, v160
	v_cvt_pk_bf16_f32 v111, v114, v115
	v_cvt_pk_bf16_f32 v113, v118, v119
	v_addc_co_u32_e32 v109, vcc, 0, v161, vcc
	global_store_dwordx4 v[108:109], v[110:113], off
	v_exp_f32_e32 v44, v44
	v_exp_f32_e32 v45, v45
	v_pk_add_f32 v[46:47], v[46:47], 1.0 op_sel_hi:[1,0]
	v_pk_add_f32 v[42:43], v[42:43], 1.0 op_sel_hi:[1,0]
	v_pk_add_f32 v[48:49], v[48:49], 1.0 op_sel_hi:[1,0]
	v_rcp_f32_e32 v46, v46
	v_rcp_f32_e32 v47, v47
	v_pk_add_f32 v[44:45], v[44:45], 1.0 op_sel_hi:[1,0]
	v_rcp_f32_e32 v42, v42
	v_rcp_f32_e32 v43, v43
	v_rcp_f32_e32 v48, v48
	v_rcp_f32_e32 v49, v49
	v_rcp_f32_e32 v44, v44
	v_rcp_f32_e32 v45, v45
	v_pk_add_f32 v[32:33], v[32:33], v[24:25]
	v_pk_add_f32 v[30:31], v[30:31], v[22:23]
	v_pk_add_f32 v[28:29], v[28:29], v[16:17]
	v_pk_add_f32 v[26:27], v[26:27], v[14:15]
	v_pk_mul_f32 v[30:31], v[30:31], s[74:75] op_sel_hi:[1,0]
	v_pk_mul_f32 v[32:33], v[32:33], s[74:75] op_sel_hi:[1,0]
	v_pk_mul_f32 v[26:27], v[26:27], s[74:75] op_sel_hi:[1,0]
	v_pk_mul_f32 v[28:29], v[28:29], s[74:75] op_sel_hi:[1,0]
	v_exp_f32_e32 v30, v30
	v_exp_f32_e32 v31, v31
	v_exp_f32_e32 v32, v32
	v_exp_f32_e32 v33, v33
	v_exp_f32_e32 v26, v26
	v_exp_f32_e32 v27, v27
	v_exp_f32_e32 v28, v28
	v_exp_f32_e32 v29, v29
	v_pk_add_f32 v[30:31], v[30:31], 1.0 op_sel_hi:[1,0]
	v_pk_add_f32 v[32:33], v[32:33], 1.0 op_sel_hi:[1,0]
	v_pk_add_f32 v[26:27], v[26:27], 1.0 op_sel_hi:[1,0]
	v_pk_add_f32 v[28:29], v[28:29], 1.0 op_sel_hi:[1,0]
	v_rcp_f32_e32 v30, v30
	v_rcp_f32_e32 v31, v31
	v_rcp_f32_e32 v32, v32
	v_rcp_f32_e32 v33, v33
	v_rcp_f32_e32 v26, v26
	v_rcp_f32_e32 v27, v27
	v_rcp_f32_e32 v28, v28
	v_rcp_f32_e32 v29, v29
	v_pk_add_f32 v[18:19], v[18:19], v[38:39]
	v_pk_add_f32 v[20:21], v[20:21], v[40:41]
	v_pk_mul_f32 v[18:19], v[18:19], s[74:75] op_sel_hi:[1,0]
	v_pk_add_f32 v[12:13], v[12:13], v[36:37]
	v_pk_add_f32 v[10:11], v[10:11], v[34:35]
	v_pk_mul_f32 v[20:21], v[20:21], s[74:75] op_sel_hi:[1,0]
	v_exp_f32_e32 v18, v18
	v_exp_f32_e32 v19, v19
	v_pk_mul_f32 v[10:11], v[10:11], s[74:75] op_sel_hi:[1,0]
	v_pk_mul_f32 v[12:13], v[12:13], s[74:75] op_sel_hi:[1,0]
	v_exp_f32_e32 v20, v20
	v_exp_f32_e32 v21, v21
	v_exp_f32_e32 v10, v10
	v_exp_f32_e32 v11, v11
	v_exp_f32_e32 v12, v12
	v_exp_f32_e32 v13, v13
	v_pk_add_f32 v[18:19], v[18:19], 1.0 op_sel_hi:[1,0]
	v_pk_add_f32 v[20:21], v[20:21], 1.0 op_sel_hi:[1,0]
	v_rcp_f32_e32 v18, v18
	v_rcp_f32_e32 v19, v19
	v_pk_add_f32 v[10:11], v[10:11], 1.0 op_sel_hi:[1,0]
	v_pk_add_f32 v[12:13], v[12:13], 1.0 op_sel_hi:[1,0]
	v_rcp_f32_e32 v20, v20
	v_rcp_f32_e32 v21, v21
	v_rcp_f32_e32 v10, v10
	v_rcp_f32_e32 v11, v11
	v_rcp_f32_e32 v12, v12
	v_rcp_f32_e32 v13, v13
	v_pk_add_f32 v[8:9], v[8:9], v[24:25]
	v_pk_add_f32 v[6:7], v[6:7], v[22:23]
	v_pk_add_f32 v[4:5], v[4:5], v[16:17]
	v_pk_add_f32 v[2:3], v[2:3], v[14:15]
	v_pk_mul_f32 v[6:7], v[6:7], s[74:75] op_sel_hi:[1,0]
	v_pk_mul_f32 v[8:9], v[8:9], s[74:75] op_sel_hi:[1,0]
	v_pk_mul_f32 v[2:3], v[2:3], s[74:75] op_sel_hi:[1,0]
	v_pk_mul_f32 v[4:5], v[4:5], s[74:75] op_sel_hi:[1,0]
	v_exp_f32_e32 v6, v6
	s_waitcnt vmcnt(14)
	v_mov_b32_e32 v110, v222
	v_mov_b32_e32 v111, v223
	v_mov_b32_e32 v112, v224
	v_mov_b32_e32 v113, v225
	global_load_dwordx4 v[222:225], v[242:243], off offset:256
	v_lshlrev_b32_e32 v114, 16, v110
	v_and_b32_e32 v115, 0xffff0000, v110
	v_lshlrev_b32_e32 v110, 16, v111
	v_and_b32_e32 v111, 0xffff0000, v111
	v_lshlrev_b32_e32 v116, 16, v112
	v_and_b32_e32 v117, 0xffff0000, v112
	v_lshlrev_b32_e32 v112, 16, v113
	v_and_b32_e32 v113, 0xffff0000, v113
	v_pk_mul_f32 v[106:107], v[106:107], v[110:111]
	v_pk_mul_f32 v[104:105], v[104:105], v[114:115]
	v_pk_mul_f32 v[110:111], v[102:103], v[112:113]
	v_pk_mul_f32 v[102:103], v[100:101], v[116:117]
	v_cvt_pk_bf16_f32 v100, v104, v105
	v_cvt_pk_bf16_f32 v101, v106, v107
	v_cvt_pk_bf16_f32 v102, v102, v103
	v_cvt_pk_bf16_f32 v103, v110, v111
	global_store_dwordx4 v[108:109], v[100:103], off offset:256
	v_exp_f32_e32 v7, v7
	v_exp_f32_e32 v8, v8
	v_add_co_u32_e32 v100, vcc, s93, v162
	v_exp_f32_e32 v9, v9
	s_nop 0
	v_addc_co_u32_e32 v101, vcc, 0, v163, vcc
	v_exp_f32_e32 v2, v2
	v_exp_f32_e32 v3, v3
	v_exp_f32_e32 v4, v4
	v_exp_f32_e32 v5, v5
	v_pk_add_f32 v[6:7], v[6:7], 1.0 op_sel_hi:[1,0]
	v_pk_add_f32 v[8:9], v[8:9], 1.0 op_sel_hi:[1,0]
	v_pk_add_f32 v[2:3], v[2:3], 1.0 op_sel_hi:[1,0]
	v_pk_add_f32 v[4:5], v[4:5], 1.0 op_sel_hi:[1,0]
	v_rcp_f32_e32 v6, v6
	v_rcp_f32_e32 v7, v7
	v_rcp_f32_e32 v8, v8
	v_rcp_f32_e32 v9, v9
	v_rcp_f32_e32 v2, v2
	v_rcp_f32_e32 v3, v3
	v_rcp_f32_e32 v4, v4
	v_rcp_f32_e32 v5, v5
	s_waitcnt vmcnt(15)
; #define GAS __attribute__((address_space(1)))
; __device__ __forceinline__ u32x4 pack8(f32x4 v0, f32x4 v1) { u32x4 w; w.x = cvt_pk_bf16(v0[0], v0[1]); w.y = cvt_pk_bf16(v0[2], v0[3]); w.z = cvt_pk_bf16(v1[0], v1[1]); w.w = cvt_pk_bf16(v1[2], v1[3]); return w; }
; __device__ __forceinline__ void unpack8(u32x4 w, f32x4& v0, f32x4& v1) { v0 = (f32x4){bflo(w.x), bfhi(w.x), bflo(w.y), bfhi(w.y)}; v1 = (f32x4){bflo(w.z), bfhi(w.z), bflo(w.w), bfhi(w.w)}; }
; #define GAS __attribute__((address_space(1)))
;     __device__ __forceinline__ void operator()(const f32x4 (&acc)[2][2][4][2], const Unit& u, int wr, int wc, int fr, int fq) const {
;     ...
; #pragma unroll
;         for (int ai = 0; ai < 2; ++ai)
; #pragma unroll
;             for (int m = 0; m < 4; ++m) { const size_t off = (size_t)(ai * HALF + m * 16) * 1024;
; #pragma unroll
;                 for (int bj = 0; bj < 2; ++bj) { f32x4 z0, z1; unpack8(*(const GAS u32x4*)(zb + off + bj * HALF), z0, z1);
;                     const f32x4 v0 = z0 * sigmoid4(acc[ai][bj][m][0] + bv[bj][0]), v1 = z1 * sigmoid4(acc[ai][bj][m][1] + bv[bj][1]);
;                     *(GAS u32x4*)(sob + off + bj * HALF) = pack8(v0, v1); } }
	v_mov_b32_e32 v102, v226
	v_mov_b32_e32 v103, v227
	v_mov_b32_e32 v104, v228
	v_mov_b32_e32 v105, v229
	v_lshlrev_b32_e32 v106, 16, v102
	v_and_b32_e32 v107, 0xffff0000, v102
	v_lshlrev_b32_e32 v108, 16, v104
	v_and_b32_e32 v109, 0xffff0000, v104
	v_lshlrev_b32_e32 v102, 16, v103
	v_and_b32_e32 v103, 0xffff0000, v103
	v_lshlrev_b32_e32 v104, 16, v105
	v_and_b32_e32 v105, 0xffff0000, v105
	v_pk_mul_f32 v[94:95], v[94:95], v[106:107]
	v_pk_mul_f32 v[90:91], v[90:91], v[108:109]
	v_pk_mul_f32 v[96:97], v[96:97], v[102:103]
	v_pk_mul_f32 v[102:103], v[92:93], v[104:105]
	v_cvt_pk_bf16_f32 v92, v94, v95
	v_cvt_pk_bf16_f32 v94, v90, v91
	v_add_co_u32_e32 v90, vcc, s93, v160
	v_cvt_pk_bf16_f32 v93, v96, v97
	v_cvt_pk_bf16_f32 v95, v102, v103
	v_addc_co_u32_e32 v91, vcc, 0, v161, vcc
	global_store_dwordx4 v[90:91], v[92:95], off
	s_waitcnt vmcnt(15)
	v_mov_b32_e32 v92, v230
	v_mov_b32_e32 v93, v231
	v_mov_b32_e32 v94, v232
	v_mov_b32_e32 v95, v233
	v_lshlrev_b32_e32 v96, 16, v92
	v_and_b32_e32 v97, 0xffff0000, v92
	v_lshlrev_b32_e32 v92, 16, v93
	v_and_b32_e32 v93, 0xffff0000, v93
	v_lshlrev_b32_e32 v100, 16, v94
	v_and_b32_e32 v101, 0xffff0000, v94
	v_lshlrev_b32_e32 v94, 16, v95
	v_and_b32_e32 v95, 0xffff0000, v95
	v_pk_mul_f32 v[88:89], v[88:89], v[92:93]
	v_pk_mul_f32 v[86:87], v[86:87], v[96:97]
	v_pk_mul_f32 v[92:93], v[84:85], v[94:95]
	v_pk_mul_f32 v[84:85], v[82:83], v[100:101]
	v_cvt_pk_bf16_f32 v82, v86, v87
	v_cvt_pk_bf16_f32 v83, v88, v89
	v_cvt_pk_bf16_f32 v84, v84, v85
	v_cvt_pk_bf16_f32 v85, v92, v93
	global_store_dwordx4 v[90:91], v[82:85], off offset:256
	s_nop 1
	v_add_co_u32_e32 v82, vcc, s49, v162
	s_nop 1
	v_addc_co_u32_e32 v83, vcc, 0, v163, vcc
	s_waitcnt vmcnt(15)
	v_mov_b32_e32 v84, v234
	v_mov_b32_e32 v85, v235
	v_mov_b32_e32 v86, v236
	v_mov_b32_e32 v87, v237
	v_lshlrev_b32_e32 v88, 16, v84
	v_and_b32_e32 v89, 0xffff0000, v84
	v_lshlrev_b32_e32 v90, 16, v86
	v_and_b32_e32 v91, 0xffff0000, v86
	v_lshlrev_b32_e32 v84, 16, v85
	v_and_b32_e32 v85, 0xffff0000, v85
	v_lshlrev_b32_e32 v86, 16, v87
	v_and_b32_e32 v87, 0xffff0000, v87
	v_pk_mul_f32 v[78:79], v[78:79], v[88:89]
	v_pk_mul_f32 v[74:75], v[74:75], v[90:91]
	v_pk_mul_f32 v[80:81], v[80:81], v[84:85]
	v_pk_mul_f32 v[84:85], v[76:77], v[86:87]
	v_cvt_pk_bf16_f32 v76, v78, v79
	v_cvt_pk_bf16_f32 v78, v74, v75
	v_add_co_u32_e32 v74, vcc, s49, v160
	v_cvt_pk_bf16_f32 v77, v80, v81
	v_cvt_pk_bf16_f32 v79, v84, v85
	v_addc_co_u32_e32 v75, vcc, 0, v161, vcc
	global_store_dwordx4 v[74:75], v[76:79], off
	s_waitcnt vmcnt(15)
	v_mov_b32_e32 v76, v238
	v_mov_b32_e32 v77, v239
	v_mov_b32_e32 v78, v240
	v_mov_b32_e32 v79, v241
	v_lshlrev_b32_e32 v80, 16, v76
	v_and_b32_e32 v81, 0xffff0000, v76
	v_lshlrev_b32_e32 v76, 16, v77
	v_and_b32_e32 v77, 0xffff0000, v77
	v_lshlrev_b32_e32 v82, 16, v78
	v_and_b32_e32 v83, 0xffff0000, v78
	v_lshlrev_b32_e32 v78, 16, v79
	v_and_b32_e32 v79, 0xffff0000, v79
	v_pk_mul_f32 v[72:73], v[72:73], v[76:77]
	v_pk_mul_f32 v[70:71], v[70:71], v[80:81]
	v_pk_mul_f32 v[76:77], v[68:69], v[78:79]
	v_pk_mul_f32 v[68:69], v[66:67], v[82:83]
	v_cvt_pk_bf16_f32 v66, v70, v71
	v_cvt_pk_bf16_f32 v67, v72, v73
	v_cvt_pk_bf16_f32 v68, v68, v69
	v_cvt_pk_bf16_f32 v69, v76, v77
	global_store_dwordx4 v[74:75], v[66:69], off offset:256
	s_nop 1
	v_add_co_u32_e32 v66, vcc, s50, v162
	s_nop 1
	v_addc_co_u32_e32 v67, vcc, 0, v163, vcc
	s_waitcnt vmcnt(15)
	v_mov_b32_e32 v68, v184
	v_mov_b32_e32 v69, v185
	v_mov_b32_e32 v70, v186
	v_mov_b32_e32 v71, v187
	v_lshlrev_b32_e32 v72, 16, v68
	v_and_b32_e32 v73, 0xffff0000, v68
	v_lshlrev_b32_e32 v74, 16, v70
	v_and_b32_e32 v75, 0xffff0000, v70
	v_lshlrev_b32_e32 v68, 16, v69
	v_and_b32_e32 v69, 0xffff0000, v69
	v_lshlrev_b32_e32 v70, 16, v71
	v_and_b32_e32 v71, 0xffff0000, v71
	v_pk_mul_f32 v[62:63], v[62:63], v[72:73]
	v_pk_mul_f32 v[58:59], v[58:59], v[74:75]
	v_pk_mul_f32 v[64:65], v[64:65], v[68:69]
	v_pk_mul_f32 v[68:69], v[60:61], v[70:71]
	v_cvt_pk_bf16_f32 v60, v62, v63
	v_cvt_pk_bf16_f32 v62, v58, v59
	v_add_co_u32_e32 v58, vcc, s50, v160
	v_cvt_pk_bf16_f32 v61, v64, v65
	v_cvt_pk_bf16_f32 v63, v68, v69
	v_addc_co_u32_e32 v59, vcc, 0, v161, vcc
	global_store_dwordx4 v[58:59], v[60:63], off
	s_waitcnt vmcnt(14)
; #define GAS __attribute__((address_space(1)))
; __device__ __forceinline__ u32x4 pack8(f32x4 v0, f32x4 v1) { u32x4 w; w.x = cvt_pk_bf16(v0[0], v0[1]); w.y = cvt_pk_bf16(v0[2], v0[3]); w.z = cvt_pk_bf16(v1[0], v1[1]); w.w = cvt_pk_bf16(v1[2], v1[3]); return w; }
; __device__ __forceinline__ void unpack8(u32x4 w, f32x4& v0, f32x4& v1) { v0 = (f32x4){bflo(w.x), bfhi(w.x), bflo(w.y), bfhi(w.y)}; v1 = (f32x4){bflo(w.z), bfhi(w.z), bflo(w.w), bfhi(w.w)}; }
; #define GAS __attribute__((address_space(1)))
;     __device__ __forceinline__ void operator()(const f32x4 (&acc)[2][2][4][2], const Unit& u, int wr, int wc, int fr, int fq) const {
;     ...
; #pragma unroll
;         for (int ai = 0; ai < 2; ++ai)
; #pragma unroll
;             for (int m = 0; m < 4; ++m) { const size_t off = (size_t)(ai * HALF + m * 16) * 1024;
; #pragma unroll
;                 for (int bj = 0; bj < 2; ++bj) { f32x4 z0, z1; unpack8(*(const GAS u32x4*)(zb + off + bj * HALF), z0, z1);
;                     const f32x4 v0 = z0 * sigmoid4(acc[ai][bj][m][0] + bv[bj][0]), v1 = z1 * sigmoid4(acc[ai][bj][m][1] + bv[bj][1]);
;                     *(GAS u32x4*)(sob + off + bj * HALF) = pack8(v0, v1); } }
	v_mov_b32_e32 v60, v188
	v_mov_b32_e32 v61, v189
	v_mov_b32_e32 v62, v190
	v_mov_b32_e32 v63, v191
	v_lshlrev_b32_e32 v64, 16, v60
	v_and_b32_e32 v65, 0xffff0000, v60
	v_lshlrev_b32_e32 v60, 16, v61
	v_and_b32_e32 v61, 0xffff0000, v61
	v_lshlrev_b32_e32 v66, 16, v62
	v_and_b32_e32 v67, 0xffff0000, v62
	v_lshlrev_b32_e32 v62, 16, v63
	v_and_b32_e32 v63, 0xffff0000, v63
	v_pk_mul_f32 v[56:57], v[56:57], v[60:61]
	v_pk_mul_f32 v[54:55], v[54:55], v[64:65]
	v_pk_mul_f32 v[60:61], v[52:53], v[62:63]
	v_pk_mul_f32 v[52:53], v[50:51], v[66:67]
	v_cvt_pk_bf16_f32 v50, v54, v55
	v_cvt_pk_bf16_f32 v51, v56, v57
	v_cvt_pk_bf16_f32 v52, v52, v53
	v_cvt_pk_bf16_f32 v53, v60, v61
	global_store_dwordx4 v[58:59], v[50:53], off offset:256
	s_nop 1
	v_add_co_u32_e32 v50, vcc, s51, v162
	s_nop 1
	v_addc_co_u32_e32 v51, vcc, 0, v163, vcc
	s_waitcnt vmcnt(13)
	v_mov_b32_e32 v52, v192
	v_mov_b32_e32 v53, v193
	v_mov_b32_e32 v54, v194
	v_mov_b32_e32 v55, v195
	v_lshlrev_b32_e32 v56, 16, v52
	v_and_b32_e32 v57, 0xffff0000, v52
	v_lshlrev_b32_e32 v58, 16, v54
	v_and_b32_e32 v59, 0xffff0000, v54
	v_lshlrev_b32_e32 v52, 16, v53
	v_and_b32_e32 v53, 0xffff0000, v53
	v_lshlrev_b32_e32 v54, 16, v55
	v_and_b32_e32 v55, 0xffff0000, v55
	v_pk_mul_f32 v[46:47], v[46:47], v[56:57]
	v_pk_mul_f32 v[42:43], v[42:43], v[58:59]
	v_pk_mul_f32 v[48:49], v[48:49], v[52:53]
	v_pk_mul_f32 v[52:53], v[44:45], v[54:55]
	v_cvt_pk_bf16_f32 v44, v46, v47
	v_cvt_pk_bf16_f32 v46, v42, v43
	v_add_co_u32_e32 v42, vcc, s51, v160
	v_cvt_pk_bf16_f32 v45, v48, v49
	v_cvt_pk_bf16_f32 v47, v52, v53
	v_addc_co_u32_e32 v43, vcc, 0, v161, vcc
	global_store_dwordx4 v[42:43], v[44:47], off
	s_waitcnt vmcnt(12)
	v_mov_b32_e32 v44, v196
	v_mov_b32_e32 v45, v197
	v_mov_b32_e32 v46, v198
	v_mov_b32_e32 v47, v199
	v_lshlrev_b32_e32 v48, 16, v44
	v_and_b32_e32 v49, 0xffff0000, v44
	v_lshlrev_b32_e32 v44, 16, v45
	v_and_b32_e32 v45, 0xffff0000, v45
	v_lshlrev_b32_e32 v50, 16, v46
	v_and_b32_e32 v51, 0xffff0000, v46
	v_lshlrev_b32_e32 v46, 16, v47
	v_and_b32_e32 v47, 0xffff0000, v47
	v_pk_mul_f32 v[32:33], v[32:33], v[44:45]
	v_pk_mul_f32 v[30:31], v[30:31], v[48:49]
	v_pk_mul_f32 v[44:45], v[28:29], v[46:47]
	v_pk_mul_f32 v[28:29], v[26:27], v[50:51]
	v_cvt_pk_bf16_f32 v26, v30, v31
	v_cvt_pk_bf16_f32 v27, v32, v33
	v_cvt_pk_bf16_f32 v28, v28, v29
	v_cvt_pk_bf16_f32 v29, v44, v45
	global_store_dwordx4 v[42:43], v[26:29], off offset:256
	s_nop 1
	v_add_co_u32_e32 v26, vcc, s66, v162
	s_nop 1
	v_addc_co_u32_e32 v27, vcc, 0, v163, vcc
	s_waitcnt vmcnt(11)
	v_mov_b32_e32 v28, v200
	v_mov_b32_e32 v29, v201
	v_mov_b32_e32 v30, v202
	v_mov_b32_e32 v31, v203
	v_lshlrev_b32_e32 v32, 16, v28
	v_and_b32_e32 v33, 0xffff0000, v28
	v_lshlrev_b32_e32 v28, 16, v29
	v_and_b32_e32 v29, 0xffff0000, v29
	v_lshlrev_b32_e32 v42, 16, v30
	v_and_b32_e32 v43, 0xffff0000, v30
	v_lshlrev_b32_e32 v30, 16, v31
	v_and_b32_e32 v31, 0xffff0000, v31
	v_pk_mul_f32 v[18:19], v[18:19], v[32:33]
	v_pk_mul_f32 v[20:21], v[20:21], v[28:29]
	v_pk_mul_f32 v[28:29], v[12:13], v[30:31]
	v_pk_mul_f32 v[12:13], v[10:11], v[42:43]
	v_cvt_pk_bf16_f32 v10, v18, v19
	v_add_co_u32_e32 v18, vcc, s66, v160
	v_cvt_pk_bf16_f32 v11, v20, v21
	v_cvt_pk_bf16_f32 v12, v12, v13
	v_cvt_pk_bf16_f32 v13, v28, v29
	v_addc_co_u32_e32 v19, vcc, 0, v161, vcc
	global_store_dwordx4 v[18:19], v[10:13], off
	s_andn2_b64 vcc, exec, s[18:19]
	s_waitcnt vmcnt(10)
	v_mov_b32_e32 v10, v222
	v_mov_b32_e32 v11, v223
	v_mov_b32_e32 v12, v224
	v_mov_b32_e32 v13, v225
	v_lshlrev_b32_e32 v20, 16, v10
	v_and_b32_e32 v21, 0xffff0000, v10
	v_lshlrev_b32_e32 v10, 16, v11
	v_and_b32_e32 v11, 0xffff0000, v11
	v_lshlrev_b32_e32 v26, 16, v12
	v_and_b32_e32 v27, 0xffff0000, v12
	v_lshlrev_b32_e32 v12, 16, v13
	v_and_b32_e32 v13, 0xffff0000, v13
	v_pk_mul_f32 v[8:9], v[8:9], v[10:11]
	v_pk_mul_f32 v[6:7], v[6:7], v[20:21]
	v_pk_mul_f32 v[10:11], v[4:5], v[12:13]
	v_pk_mul_f32 v[4:5], v[2:3], v[26:27]
	v_cvt_pk_bf16_f32 v2, v6, v7
	v_cvt_pk_bf16_f32 v3, v8, v9
	v_cvt_pk_bf16_f32 v4, v4, v5
	v_cvt_pk_bf16_f32 v5, v10, v11
	global_store_dwordx4 v[18:19], v[2:5], off offset:256
	s_cbranch_vccnz .LBB0_923
	s_andn2_b64 vcc, exec, s[6:7]
	s_cbranch_vccnz .LBB0_922
	s_barrier
	s_branch .LBB0_922
